# MoBA gate top-3 update made branchless (3 compares, 5 cndmask, 2 med3, 1 max; no divergent branches or phi copies)
# speedup vs baseline: 1.0015x; 1.0015x over previous
.LBB0_390:
	ds_read_b128 v[60:63], v54
	ds_read_b128 v[68:71], v54 offset:16
	ds_read_b128 v[72:75], v54 offset:64
	ds_read_b128 v[76:79], v54 offset:80
	ds_read_b128 v[80:83], v54 offset:128
	s_waitcnt lgkmcnt(4)
	v_fma_f32 v64, v60, v26, 0
	v_fmac_f32_e32 v64, v61, v27
	v_fmac_f32_e32 v64, v62, v28
	v_fmac_f32_e32 v64, v63, v29
	s_waitcnt lgkmcnt(3)
	v_fmac_f32_e32 v64, v68, v30
	v_fmac_f32_e32 v64, v69, v31
	v_fmac_f32_e32 v64, v70, v32
	v_fmac_f32_e32 v64, v71, v33
	s_waitcnt lgkmcnt(2)
	v_fmac_f32_e32 v64, v72, v38
	v_fmac_f32_e32 v64, v73, v39
	v_fmac_f32_e32 v64, v74, v40
	v_fmac_f32_e32 v64, v75, v41
	s_waitcnt lgkmcnt(1)
	v_fmac_f32_e32 v64, v76, v42
	v_fmac_f32_e32 v64, v77, v43
	v_fmac_f32_e32 v64, v78, v44
	v_fmac_f32_e32 v64, v79, v45
	ds_read_b128 v[60:63], v54 offset:144
	ds_read_b128 v[68:71], v54 offset:192
	s_waitcnt lgkmcnt(2)
	v_fmac_f32_e32 v64, v80, v46
	v_fmac_f32_e32 v64, v81, v47
	v_fmac_f32_e32 v64, v82, v48
	v_fmac_f32_e32 v64, v83, v49
	s_waitcnt lgkmcnt(1)
	v_fmac_f32_e32 v64, v60, v50
	v_fmac_f32_e32 v64, v61, v51
	v_fmac_f32_e32 v64, v62, v52
	v_fmac_f32_e32 v64, v63, v53
	ds_read_b128 v[60:63], v54 offset:208
	s_waitcnt lgkmcnt(1)
	v_pk_mul_f32 v[36:37], v[68:69], v[18:19]
	s_lshl_b32 s50, 1, s49
	v_add_f32_e32 v36, v36, v64
	v_add_f32_e32 v64, v37, v36
	v_pk_mul_f32 v[36:37], v[70:71], v[20:21]
	s_nop 0
	v_add_f32_e32 v36, v36, v64
	v_add_f32_e32 v64, v37, v36
	s_waitcnt lgkmcnt(0)
	v_pk_mul_f32 v[36:37], v[60:61], v[22:23]
	v_add_f32_e32 v36, v36, v64
	v_add_f32_e32 v60, v37, v36
	v_pk_mul_f32 v[36:37], v[62:63], v[24:25]
	s_nop 0
	v_add_f32_e32 v36, v36, v60
	v_add_f32_e32 v36, v37, v36
	v_mov_b32_e32 v37, v36
	s_nop 1
	v_permlane32_swap_b32_e32 v36, v37
	v_add_f32_e32 v60, v36, v37
	v_mov_b32_e32 v37, s50
	v_cmp_gt_f32_e64 s[8:9], v60, v55
	v_cmp_gt_f32_e64 s[42:43], v60, v56
	v_cmp_gt_f32_e32 vcc, v60, v59
	s_add_i32 s49, s49, 1
	v_add_u32_e32 v54, 0x100, v54
	v_cndmask_b32_e32 v35, v35, v37, vcc
	v_med3_f32 v59, v60, v56, v59
	v_cndmask_b32_e64 v35, v35, v57, s[42:43]
	v_cndmask_b32_e64 v57, v57, v37, s[42:43]
	v_med3_f32 v56, v60, v55, v56
	v_cndmask_b32_e64 v57, v57, v58, s[8:9]
	v_cndmask_b32_e64 v58, v58, v37, s[8:9]
	v_max_f32_e32 v55, v55, v60
	s_cmp_lg_u32 s82, s49
	s_cbranch_scc1 .LBB0_390
	v_mov_b32_e32 v37, v58
	v_mov_b32_e32 v36, v57
	s_branch .LBB0_400
